# speedup vs baseline: 1.0015x; 1.0015x over previous
; #define LAS __attribute__((address_space(3)))
; __global__ void __launch_bounds__(512, 2) fwd_kernel(KP p) {
;     ...
;     const int wave = __builtin_amdgcn_readfirstlane((int)threadIdx.x >> 6);
;     const int G = gridDim.x, b = blockIdx.x;
;     const int gw = b * 8 + wave, NGW = G * 8;
;     const int gw2 = wave * G + b;
;     const int NGT = G * 512;
;     ...
;     unsigned char* ws = p.ws;
;     float* MOD = (float*)(ws + WS_MOD); float* MODP = (float*)(ws + WS_MODP);
;     float* ROPEC = (float*)(ws + WS_ROPEC); float* ROPES = (float*)(ws + WS_ROPES);
;     f32x2* LP = (f32x2*)(ws + WS_LP); f32x2* BB = (f32x2*)(ws + WS_BB); float* KF = (float*)(ws + WS_KF);
;     float* SSQA = (float*)(ws + WS_SSQA); float* SSQS = (float*)(ws + WS_SSQS); float* KR = (float*)(ws + WS_KR); float* KRB = (float*)(ws + WS_KRB);
;     bf16_t* WIN = (bf16_t*)(ws + WS_WIN); bf16_t* WUKV = (bf16_t*)(ws + WS_WUKV); bf16_t* WGLU = (bf16_t*)(ws + WS_WGLU); bf16_t* WOT = (bf16_t*)(ws + WS_WO);
;     bf16_t* W13 = (bf16_t*)(ws + WS_W13); bf16_t* W2T = (bf16_t*)(ws + WS_W2); bf16_t* BMAT = (bf16_t*)(ws + WS_BMAT); bf16_t* BT2 = (bf16_t*)(ws + WS_BT2);
;     bf16_t* Hb = (bf16_t*)(ws + WS_H); bf16_t* Qb = (bf16_t*)(ws + WS_Q); bf16_t* Kb = (bf16_t*)(ws + WS_K); bf16_t* Vb = (bf16_t*)(ws + WS_V);
;     bf16_t* A2 = (bf16_t*)(ws + WS_A2); bf16_t* CKV = (bf16_t*)(ws + WS_CKV); bf16_t* MIX = (bf16_t*)(ws + WS_MIXED); bf16_t* Gb = (bf16_t*)(ws + WS_G);
;     float* SSQX = (float*)(ws + WS_KR); float* R2 = (float*)(ws + WS_KRB); float* CB = (float*)(ws + WS_KF);
;     bf16_t* X1B = (bf16_t*)(ws + WS_X1B);
;     float* SSQC = (float*)(ws + WS_SSQS); float* SSQR = (float*)(ws + WS_SSQA);
;     float* FLOC = (float*)((unsigned char*)p.out + OUT_FLOC); bf16_t* YG = (bf16_t*)((unsigned char*)p.out + OUT_YG);
;     const int lo = p.ph_lo, hi_ph = p.ph_hi;
;     ...
;     if (lo < 0) { __threadfence(); cg::this_grid().sync(); }
;     volatile LAS unsigned* xst = (volatile LAS unsigned*)(lds + XTRA_OFF + 15360);
;     { const int t0 = (int)threadIdx.x; if (t0 < 2) xst[t0] = 0u; }
;     __syncthreads();
;     const XcdBarrier xbar = xcd_barrier_post((unsigned*)ws, xst);
;     ...
;         for (int e = tid; e < NSEQ * DM; e += 512) { const int s = e / DM, k = e % DM; const float c = (s < 4) ? p.in[I_CP][s * DM + k] : p.in[I_CS][k]; sc[e] = c / (1.f + __expf(-c)); }
;         __syncthreads();
.LBB0_6:
	s_or_b64 exec, exec, s[4:5]
	s_load_dwordx16 s[16:31], s[0:1], 0x0
	s_lshr_b32 s5, s40, 6
	s_lshl_b32 s4, s2, 3
	s_add_i32 s90, s5, s4
	s_mul_i32 s4, s5, s3
	s_waitcnt lgkmcnt(0)
	v_writelane_b32 v254, s16, 10
	s_lshl_b32 s94, s3, 3
	s_add_i32 s33, s4, s2
	v_writelane_b32 v254, s17, 11
	v_writelane_b32 v254, s18, 12
	v_writelane_b32 v254, s19, 13
	v_writelane_b32 v254, s20, 14
	v_writelane_b32 v254, s21, 15
	v_writelane_b32 v254, s22, 16
	v_writelane_b32 v254, s23, 17
	v_writelane_b32 v254, s24, 18
	v_writelane_b32 v254, s25, 19
	v_writelane_b32 v254, s26, 20
	v_writelane_b32 v254, s27, 21
	v_writelane_b32 v254, s28, 22
	v_writelane_b32 v254, s29, 23
	v_writelane_b32 v254, s30, 24
	v_writelane_b32 v254, s31, 25
	s_load_dwordx16 s[16:31], s[0:1], 0x40
	s_lshl_b32 s42, s3, 9
	s_load_dwordx16 s[64:79], s[0:1], 0x80
	s_waitcnt lgkmcnt(0)
	v_writelane_b32 v254, s16, 26
	s_nop 1
	v_writelane_b32 v254, s17, 27
	v_writelane_b32 v254, s18, 28
	v_writelane_b32 v254, s19, 29
	v_writelane_b32 v254, s20, 30
	v_writelane_b32 v254, s21, 31
	v_writelane_b32 v254, s22, 32
	v_writelane_b32 v254, s23, 33
	v_writelane_b32 v254, s24, 34
	v_writelane_b32 v254, s25, 35
	v_writelane_b32 v254, s26, 36
	v_writelane_b32 v254, s27, 37
	v_writelane_b32 v254, s28, 38
	v_writelane_b32 v254, s29, 39
	v_writelane_b32 v254, s30, 40
	v_writelane_b32 v254, s31, 41
	s_add_u32 s28, s12, 0x200000
	s_addc_u32 s29, s13, 0
	s_add_u32 s22, s12, 0x900000
	s_addc_u32 s23, s13, 0
	s_add_u32 s4, s12, 0x2a00000
	v_writelane_b32 v254, s5, 42
	s_addc_u32 s5, s13, 0
	v_writelane_b32 v254, s4, 43
	s_nop 1
	v_writelane_b32 v254, s5, 44
	s_add_u32 s4, s12, 0x3700000
	s_addc_u32 s5, s13, 0
	v_writelane_b32 v254, s4, 45
	s_nop 1
	v_writelane_b32 v254, s5, 46
	s_add_u32 s4, s12, 0x3900000
	s_addc_u32 s5, s13, 0
	v_writelane_b32 v254, s4, 47
	s_nop 1
	v_writelane_b32 v254, s5, 48
	s_add_u32 s4, s12, 0x3b00000
	s_addc_u32 s5, s13, 0
	v_writelane_b32 v254, s4, 49
	s_nop 1
	v_writelane_b32 v254, s5, 50
	s_add_u32 s4, s12, 0x4300000
	s_addc_u32 s5, s13, 0
	v_writelane_b32 v254, s4, 51
	s_add_u32 s60, s12, 0x6f00000
	s_addc_u32 s61, s13, 0
	v_writelane_b32 v254, s5, 52
	v_writelane_b32 v254, s64, 53
	s_cmp_lt_i32 s14, 1
	s_cselect_b64 s[4:5], -1, 0
	v_writelane_b32 v254, s65, 54
	v_writelane_b32 v254, s66, 55
	v_writelane_b32 v254, s67, 56
	v_writelane_b32 v254, s68, 57
	v_writelane_b32 v253, s75, 0
	v_writelane_b32 v254, s69, 58
	v_writelane_b32 v253, s76, 1
	v_writelane_b32 v254, s70, 59
	v_writelane_b32 v253, s77, 2
	s_cmp_gt_i32 s15, 0
	v_writelane_b32 v254, s71, 60
	v_writelane_b32 v253, s78, 3
	s_cselect_b64 s[6:7], -1, 0
	v_writelane_b32 v254, s72, 61
	v_writelane_b32 v253, s79, 4
	s_lshl_b32 s0, s2, 9
	s_and_b32 s16, s40, 0xffffffc0
	v_writelane_b32 v254, s73, 62
	s_and_b64 s[62:63], s[4:5], s[6:7]
	v_writelane_b32 v253, s0, 5
	v_writelane_b32 v254, s74, 63
	s_andn2_b64 vcc, exec, s[62:63]
	v_writelane_b32 v253, s16, 6
	s_cbranch_vccnz .LBB0_116
	s_mov_b32 s0, 0
	s_nop 0
	v_mbcnt_lo_u32_b32 v0, -1, s0
	v_mbcnt_hi_u32_b32 v4, -1, v0
	v_add_u32_e32 v70, s16, v4
	s_movk_i32 s0, 0x2800
	v_cmp_gt_i32_e32 vcc, s0, v70
	s_and_saveexec_b64 s[0:1], vcc
	s_cbranch_execz .LBB0_14
	v_readlane_b32 s48, v254, 14
	v_readlane_b32 s49, v254, 15
	v_readlane_b32 s50, v254, 16
	v_readlane_b32 s51, v254, 17
	v_lshlrev_b32_e32 v5, 2, v70
	v_mov_b32_e32 v1, 0
	s_nop 1
	s_mov_b64 s[4:5], s[48:49]
	global_load_dword v100, v5, s[4:5]
	global_load_dword v101, v5, s[4:5] offset:2048
	s_add_u32 s4, s4, 0x1000
	s_addc_u32 s5, s5, 0
	global_load_dword v102, v5, s[4:5]
	global_load_dword v103, v5, s[4:5] offset:2048
	s_add_u32 s4, s4, 0x1000
	s_addc_u32 s5, s5, 0
	global_load_dword v104, v5, s[4:5]
	global_load_dword v105, v5, s[4:5] offset:2048
	s_add_u32 s4, s4, 0x1000
	s_addc_u32 s5, s5, 0
	global_load_dword v106, v5, s[4:5]
	global_load_dword v107, v5, s[4:5] offset:2048
	s_add_u32 s4, s4, 0x1000
	s_addc_u32 s5, s5, 0
	global_load_dword v108, v5, s[4:5]
	global_load_dword v109, v5, s[4:5] offset:2048
	s_add_u32 s4, s4, 0x1000
	s_addc_u32 s5, s5, 0
	global_load_dword v110, v5, s[4:5]
	global_load_dword v111, v5, s[4:5] offset:2048
	s_add_u32 s4, s4, 0x1000
	s_addc_u32 s5, s5, 0
	global_load_dword v112, v5, s[4:5]
	global_load_dword v113, v5, s[4:5] offset:2048
	s_add_u32 s4, s4, 0x1000
	s_addc_u32 s5, s5, 0
	global_load_dword v114, v5, s[4:5]
	global_load_dword v115, v5, s[4:5] offset:2048
	global_load_dword v116, v5, s[50:51]
	global_load_dword v117, v5, s[50:51] offset:2048
	s_add_u32 s4, s50, 0x1000
	s_addc_u32 s5, s51, 0
	global_load_dword v118, v5, s[4:5]
	global_load_dword v119, v5, s[4:5] offset:2048
	s_waitcnt vmcnt(0)
; __global__ void __launch_bounds__(512, 2) fwd_kernel(KP p) {
;     ...
;         for (int e = tid; e < NSEQ * DM; e += 512) { const int s = e / DM, k = e % DM; const float c = (s < 4) ? p.in[I_CP][s * DM + k] : p.in[I_CS][k]; sc[e] = c / (1.f + __expf(-c)); }
	v_mul_f32_e32 v2, 0xbfb8aa3b, v100
	v_exp_f32_e32 v2, v2
	s_nop 0
	v_add_f32_e32 v2, 1.0, v2
	v_div_scale_f32 v6, s[6:7], v2, v2, v100
	v_rcp_f32_e32 v7, v6
	v_div_scale_f32 v8, vcc, v100, v2, v100
	v_fma_f32 v9, -v6, v7, 1.0
	v_fmac_f32_e32 v7, v9, v7
	v_mul_f32_e32 v9, v8, v7
	v_fma_f32 v10, -v6, v9, v8
	v_fmac_f32_e32 v9, v10, v7
	v_fma_f32 v6, -v6, v9, v8
	v_div_fmas_f32 v6, v6, v7, v9
	v_div_fixup_f32 v0, v6, v2, v100
	ds_write_b32 v5, v0
	v_mul_f32_e32 v2, 0xbfb8aa3b, v101
	v_exp_f32_e32 v2, v2
	s_nop 0
	v_add_f32_e32 v2, 1.0, v2
	v_div_scale_f32 v6, s[6:7], v2, v2, v101
	v_rcp_f32_e32 v7, v6
	v_div_scale_f32 v8, vcc, v101, v2, v101
	v_fma_f32 v9, -v6, v7, 1.0
	v_fmac_f32_e32 v7, v9, v7
	v_mul_f32_e32 v9, v8, v7
	v_fma_f32 v10, -v6, v9, v8
	v_fmac_f32_e32 v9, v10, v7
	v_fma_f32 v6, -v6, v9, v8
	v_div_fmas_f32 v6, v6, v7, v9
	v_div_fixup_f32 v0, v6, v2, v101
	ds_write_b32 v5, v0 offset:2048
	v_mul_f32_e32 v2, 0xbfb8aa3b, v102
	v_exp_f32_e32 v2, v2
	s_nop 0
	v_add_f32_e32 v2, 1.0, v2
	v_div_scale_f32 v6, s[6:7], v2, v2, v102
	v_rcp_f32_e32 v7, v6
	v_div_scale_f32 v8, vcc, v102, v2, v102
	v_fma_f32 v9, -v6, v7, 1.0
	v_fmac_f32_e32 v7, v9, v7
	v_mul_f32_e32 v9, v8, v7
	v_fma_f32 v10, -v6, v9, v8
	v_fmac_f32_e32 v9, v10, v7
	v_fma_f32 v6, -v6, v9, v8
	v_div_fmas_f32 v6, v6, v7, v9
	v_div_fixup_f32 v0, v6, v2, v102
	ds_write_b32 v5, v0 offset:4096
	v_mul_f32_e32 v2, 0xbfb8aa3b, v103
	v_exp_f32_e32 v2, v2
	s_nop 0
	v_add_f32_e32 v2, 1.0, v2
	v_div_scale_f32 v6, s[6:7], v2, v2, v103
	v_rcp_f32_e32 v7, v6
	v_div_scale_f32 v8, vcc, v103, v2, v103
	v_fma_f32 v9, -v6, v7, 1.0
	v_fmac_f32_e32 v7, v9, v7
	v_mul_f32_e32 v9, v8, v7
	v_fma_f32 v10, -v6, v9, v8
	v_fmac_f32_e32 v9, v10, v7
	v_fma_f32 v6, -v6, v9, v8
	v_div_fmas_f32 v6, v6, v7, v9
	v_div_fixup_f32 v0, v6, v2, v103
	ds_write_b32 v5, v0 offset:6144
	v_mul_f32_e32 v2, 0xbfb8aa3b, v104
	v_exp_f32_e32 v2, v2
	s_nop 0
	v_add_f32_e32 v2, 1.0, v2
	v_div_scale_f32 v6, s[6:7], v2, v2, v104
	v_rcp_f32_e32 v7, v6
	v_div_scale_f32 v8, vcc, v104, v2, v104
	v_fma_f32 v9, -v6, v7, 1.0
	v_fmac_f32_e32 v7, v9, v7
	v_mul_f32_e32 v9, v8, v7
	v_fma_f32 v10, -v6, v9, v8
	v_fmac_f32_e32 v9, v10, v7
	v_fma_f32 v6, -v6, v9, v8
	v_div_fmas_f32 v6, v6, v7, v9
	v_div_fixup_f32 v0, v6, v2, v104
	ds_write_b32 v5, v0 offset:8192
	v_mul_f32_e32 v2, 0xbfb8aa3b, v105
	v_exp_f32_e32 v2, v2
	s_nop 0
	v_add_f32_e32 v2, 1.0, v2
	v_div_scale_f32 v6, s[6:7], v2, v2, v105
	v_rcp_f32_e32 v7, v6
	v_div_scale_f32 v8, vcc, v105, v2, v105
	v_fma_f32 v9, -v6, v7, 1.0
	v_fmac_f32_e32 v7, v9, v7
	v_mul_f32_e32 v9, v8, v7
	v_fma_f32 v10, -v6, v9, v8
	v_fmac_f32_e32 v9, v10, v7
	v_fma_f32 v6, -v6, v9, v8
	v_div_fmas_f32 v6, v6, v7, v9
	v_div_fixup_f32 v0, v6, v2, v105
	ds_write_b32 v5, v0 offset:10240
	v_mul_f32_e32 v2, 0xbfb8aa3b, v106
	v_exp_f32_e32 v2, v2
	s_nop 0
	v_add_f32_e32 v2, 1.0, v2
	v_div_scale_f32 v6, s[6:7], v2, v2, v106
	v_rcp_f32_e32 v7, v6
	v_div_scale_f32 v8, vcc, v106, v2, v106
	v_fma_f32 v9, -v6, v7, 1.0
	v_fmac_f32_e32 v7, v9, v7
	v_mul_f32_e32 v9, v8, v7
	v_fma_f32 v10, -v6, v9, v8
	v_fmac_f32_e32 v9, v10, v7
	v_fma_f32 v6, -v6, v9, v8
	v_div_fmas_f32 v6, v6, v7, v9
	v_div_fixup_f32 v0, v6, v2, v106
	ds_write_b32 v5, v0 offset:12288
	v_mul_f32_e32 v2, 0xbfb8aa3b, v107
	v_exp_f32_e32 v2, v2
	s_nop 0
	v_add_f32_e32 v2, 1.0, v2
	v_div_scale_f32 v6, s[6:7], v2, v2, v107
	v_rcp_f32_e32 v7, v6
	v_div_scale_f32 v8, vcc, v107, v2, v107
	v_fma_f32 v9, -v6, v7, 1.0
	v_fmac_f32_e32 v7, v9, v7
	v_mul_f32_e32 v9, v8, v7
	v_fma_f32 v10, -v6, v9, v8
	v_fmac_f32_e32 v9, v10, v7
	v_fma_f32 v6, -v6, v9, v8
	v_div_fmas_f32 v6, v6, v7, v9
	v_div_fixup_f32 v0, v6, v2, v107
	ds_write_b32 v5, v0 offset:14336
	v_mul_f32_e32 v2, 0xbfb8aa3b, v108
	v_exp_f32_e32 v2, v2
	s_nop 0
	v_add_f32_e32 v2, 1.0, v2
	v_div_scale_f32 v6, s[6:7], v2, v2, v108
	v_rcp_f32_e32 v7, v6
	v_div_scale_f32 v8, vcc, v108, v2, v108
	v_fma_f32 v9, -v6, v7, 1.0
	v_fmac_f32_e32 v7, v9, v7
	v_mul_f32_e32 v9, v8, v7
	v_fma_f32 v10, -v6, v9, v8
	v_fmac_f32_e32 v9, v10, v7
	v_fma_f32 v6, -v6, v9, v8
	v_div_fmas_f32 v6, v6, v7, v9
	v_div_fixup_f32 v0, v6, v2, v108
	ds_write_b32 v5, v0 offset:16384
	v_mul_f32_e32 v2, 0xbfb8aa3b, v109
	v_exp_f32_e32 v2, v2
	s_nop 0
	v_add_f32_e32 v2, 1.0, v2
	v_div_scale_f32 v6, s[6:7], v2, v2, v109
	v_rcp_f32_e32 v7, v6
	v_div_scale_f32 v8, vcc, v109, v2, v109
	v_fma_f32 v9, -v6, v7, 1.0
	v_fmac_f32_e32 v7, v9, v7
	v_mul_f32_e32 v9, v8, v7
	v_fma_f32 v10, -v6, v9, v8
	v_fmac_f32_e32 v9, v10, v7
	v_fma_f32 v6, -v6, v9, v8
	v_div_fmas_f32 v6, v6, v7, v9
	v_div_fixup_f32 v0, v6, v2, v109
	ds_write_b32 v5, v0 offset:18432
; __global__ void __launch_bounds__(512, 2) fwd_kernel(KP p) {
;     ...
;         for (int e = tid; e < NSEQ * DM; e += 512) { const int s = e / DM, k = e % DM; const float c = (s < 4) ? p.in[I_CP][s * DM + k] : p.in[I_CS][k]; sc[e] = c / (1.f + __expf(-c)); }
	v_mul_f32_e32 v2, 0xbfb8aa3b, v110
	v_exp_f32_e32 v2, v2
	s_nop 0
	v_add_f32_e32 v2, 1.0, v2
	v_div_scale_f32 v6, s[6:7], v2, v2, v110
	v_rcp_f32_e32 v7, v6
	v_div_scale_f32 v8, vcc, v110, v2, v110
	v_fma_f32 v9, -v6, v7, 1.0
	v_fmac_f32_e32 v7, v9, v7
	v_mul_f32_e32 v9, v8, v7
	v_fma_f32 v10, -v6, v9, v8
	v_fmac_f32_e32 v9, v10, v7
	v_fma_f32 v6, -v6, v9, v8
	v_div_fmas_f32 v6, v6, v7, v9
	v_div_fixup_f32 v0, v6, v2, v110
	ds_write_b32 v5, v0 offset:20480
	v_mul_f32_e32 v2, 0xbfb8aa3b, v111
	v_exp_f32_e32 v2, v2
	s_nop 0
	v_add_f32_e32 v2, 1.0, v2
	v_div_scale_f32 v6, s[6:7], v2, v2, v111
	v_rcp_f32_e32 v7, v6
	v_div_scale_f32 v8, vcc, v111, v2, v111
	v_fma_f32 v9, -v6, v7, 1.0
	v_fmac_f32_e32 v7, v9, v7
	v_mul_f32_e32 v9, v8, v7
	v_fma_f32 v10, -v6, v9, v8
	v_fmac_f32_e32 v9, v10, v7
	v_fma_f32 v6, -v6, v9, v8
	v_div_fmas_f32 v6, v6, v7, v9
	v_div_fixup_f32 v0, v6, v2, v111
	ds_write_b32 v5, v0 offset:22528
	v_mul_f32_e32 v2, 0xbfb8aa3b, v112
	v_exp_f32_e32 v2, v2
	s_nop 0
	v_add_f32_e32 v2, 1.0, v2
	v_div_scale_f32 v6, s[6:7], v2, v2, v112
	v_rcp_f32_e32 v7, v6
	v_div_scale_f32 v8, vcc, v112, v2, v112
	v_fma_f32 v9, -v6, v7, 1.0
	v_fmac_f32_e32 v7, v9, v7
	v_mul_f32_e32 v9, v8, v7
	v_fma_f32 v10, -v6, v9, v8
	v_fmac_f32_e32 v9, v10, v7
	v_fma_f32 v6, -v6, v9, v8
	v_div_fmas_f32 v6, v6, v7, v9
	v_div_fixup_f32 v0, v6, v2, v112
	ds_write_b32 v5, v0 offset:24576
	v_mul_f32_e32 v2, 0xbfb8aa3b, v113
	v_exp_f32_e32 v2, v2
	s_nop 0
	v_add_f32_e32 v2, 1.0, v2
	v_div_scale_f32 v6, s[6:7], v2, v2, v113
	v_rcp_f32_e32 v7, v6
	v_div_scale_f32 v8, vcc, v113, v2, v113
	v_fma_f32 v9, -v6, v7, 1.0
	v_fmac_f32_e32 v7, v9, v7
	v_mul_f32_e32 v9, v8, v7
	v_fma_f32 v10, -v6, v9, v8
	v_fmac_f32_e32 v9, v10, v7
	v_fma_f32 v6, -v6, v9, v8
	v_div_fmas_f32 v6, v6, v7, v9
	v_div_fixup_f32 v0, v6, v2, v113
	ds_write_b32 v5, v0 offset:26624
	v_mul_f32_e32 v2, 0xbfb8aa3b, v114
	v_exp_f32_e32 v2, v2
	s_nop 0
	v_add_f32_e32 v2, 1.0, v2
	v_div_scale_f32 v6, s[6:7], v2, v2, v114
	v_rcp_f32_e32 v7, v6
	v_div_scale_f32 v8, vcc, v114, v2, v114
	v_fma_f32 v9, -v6, v7, 1.0
	v_fmac_f32_e32 v7, v9, v7
	v_mul_f32_e32 v9, v8, v7
	v_fma_f32 v10, -v6, v9, v8
	v_fmac_f32_e32 v9, v10, v7
	v_fma_f32 v6, -v6, v9, v8
	v_div_fmas_f32 v6, v6, v7, v9
	v_div_fixup_f32 v0, v6, v2, v114
	ds_write_b32 v5, v0 offset:28672
	v_mul_f32_e32 v2, 0xbfb8aa3b, v115
	v_exp_f32_e32 v2, v2
	s_nop 0
	v_add_f32_e32 v2, 1.0, v2
	v_div_scale_f32 v6, s[6:7], v2, v2, v115
	v_rcp_f32_e32 v7, v6
	v_div_scale_f32 v8, vcc, v115, v2, v115
	v_fma_f32 v9, -v6, v7, 1.0
	v_fmac_f32_e32 v7, v9, v7
	v_mul_f32_e32 v9, v8, v7
	v_fma_f32 v10, -v6, v9, v8
	v_fmac_f32_e32 v9, v10, v7
	v_fma_f32 v6, -v6, v9, v8
	v_div_fmas_f32 v6, v6, v7, v9
	v_div_fixup_f32 v0, v6, v2, v115
	ds_write_b32 v5, v0 offset:30720
	v_mul_f32_e32 v2, 0xbfb8aa3b, v116
	v_exp_f32_e32 v2, v2
	s_nop 0
	v_add_f32_e32 v2, 1.0, v2
	v_div_scale_f32 v6, s[6:7], v2, v2, v116
	v_rcp_f32_e32 v7, v6
	v_div_scale_f32 v8, vcc, v116, v2, v116
	v_fma_f32 v9, -v6, v7, 1.0
	v_fmac_f32_e32 v7, v9, v7
	v_mul_f32_e32 v9, v8, v7
	v_fma_f32 v10, -v6, v9, v8
	v_fmac_f32_e32 v9, v10, v7
	v_fma_f32 v6, -v6, v9, v8
	v_div_fmas_f32 v6, v6, v7, v9
	v_div_fixup_f32 v0, v6, v2, v116
	ds_write_b32 v5, v0 offset:32768
	v_mul_f32_e32 v2, 0xbfb8aa3b, v117
	v_exp_f32_e32 v2, v2
	s_nop 0
	v_add_f32_e32 v2, 1.0, v2
	v_div_scale_f32 v6, s[6:7], v2, v2, v117
	v_rcp_f32_e32 v7, v6
	v_div_scale_f32 v8, vcc, v117, v2, v117
	v_fma_f32 v9, -v6, v7, 1.0
	v_fmac_f32_e32 v7, v9, v7
	v_mul_f32_e32 v9, v8, v7
	v_fma_f32 v10, -v6, v9, v8
	v_fmac_f32_e32 v9, v10, v7
	v_fma_f32 v6, -v6, v9, v8
	v_div_fmas_f32 v6, v6, v7, v9
	v_div_fixup_f32 v0, v6, v2, v117
	ds_write_b32 v5, v0 offset:34816
	v_mul_f32_e32 v2, 0xbfb8aa3b, v118
	v_exp_f32_e32 v2, v2
	s_nop 0
	v_add_f32_e32 v2, 1.0, v2
	v_div_scale_f32 v6, s[6:7], v2, v2, v118
	v_rcp_f32_e32 v7, v6
	v_div_scale_f32 v8, vcc, v118, v2, v118
	v_fma_f32 v9, -v6, v7, 1.0
	v_fmac_f32_e32 v7, v9, v7
	v_mul_f32_e32 v9, v8, v7
	v_fma_f32 v10, -v6, v9, v8
	v_fmac_f32_e32 v9, v10, v7
	v_fma_f32 v6, -v6, v9, v8
	v_div_fmas_f32 v6, v6, v7, v9
	v_div_fixup_f32 v0, v6, v2, v118
	ds_write_b32 v5, v0 offset:36864
	v_mul_f32_e32 v2, 0xbfb8aa3b, v119
	v_exp_f32_e32 v2, v2
	s_nop 0
	v_add_f32_e32 v2, 1.0, v2
	v_div_scale_f32 v6, s[6:7], v2, v2, v119
	v_rcp_f32_e32 v7, v6
	v_div_scale_f32 v8, vcc, v119, v2, v119
	v_fma_f32 v9, -v6, v7, 1.0
	v_fmac_f32_e32 v7, v9, v7
	v_mul_f32_e32 v9, v8, v7
	v_fma_f32 v10, -v6, v9, v8
	v_fmac_f32_e32 v9, v10, v7
	v_fma_f32 v6, -v6, v9, v8
	v_div_fmas_f32 v6, v6, v7, v9
	v_div_fixup_f32 v0, v6, v2, v119
	ds_write_b32 v5, v0 offset:38912

; __global__ void __launch_bounds__(512, 2) fwd_kernel(KP p) {
;     ...
;         for (int e = tid; e < NSEQ * DM; e += 512) { const int s = e / DM, col = e % DM; float sh = p.in[I_BADA][col], sl = p.in[I_BADA][2048 + col];
; #pragma unroll
;             for (int ks = 0; ks < 8; ++ks) { sh += MODP[(size_t)(ks * 5 + s) * 12288 + col]; sl += MODP[(size_t)(ks * 5 + s) * 12288 + 2048 + col]; }
;             a1[e] = p.in[I_GMIX][col] * (1.f + sl); b1[e] = sh; }
.LBB0_185:
	s_or_b64 exec, exec, s[0:1]
	s_movk_i32 s0, 0x2800
	v_cmp_gt_i32_e32 vcc, s0, v0
	s_and_saveexec_b64 s[0:1], vcc
	v_readlane_b32 s72, v254, 10
	v_readlane_b32 s73, v254, 11
	v_readlane_b32 s74, v254, 12
	v_readlane_b32 s75, v254, 13
	v_readlane_b32 s76, v254, 14
	v_readlane_b32 s77, v254, 15
	v_readlane_b32 s78, v254, 16
	v_readlane_b32 s79, v254, 17
	v_readlane_b32 s80, v254, 18
	v_readlane_b32 s81, v254, 19
	v_readlane_b32 s82, v254, 20
	v_readlane_b32 s83, v254, 21
	v_readlane_b32 s84, v254, 22
	v_readlane_b32 s85, v254, 23
	v_readlane_b32 s86, v254, 24
	v_readlane_b32 s87, v254, 25
	s_cbranch_execz .LBB0_205
	v_lshlrev_b32_e32 v1, 2, v0
	v_add_u32_e32 v2, 0xa000, v1
	global_load_dword v108, v1, s[82:83]
	global_load_dword v109, v1, s[82:83] offset:2048
	s_add_u32 s6, s82, 0x1000
	s_addc_u32 s7, s83, 0
	global_load_dword v110, v1, s[6:7]
	global_load_dword v111, v1, s[6:7] offset:2048
	s_add_u32 s6, s82, 0x2000
	s_addc_u32 s7, s83, 0
	global_load_dword v112, v1, s[6:7]
	global_load_dword v113, v1, s[6:7] offset:2048
	s_add_u32 s6, s82, 0x3000
	s_addc_u32 s7, s83, 0
	global_load_dword v114, v1, s[6:7]
	global_load_dword v115, v1, s[6:7] offset:2048
	global_load_dword v116, v1, s[84:85]
	global_load_dword v117, v1, s[84:85] offset:2048
	s_add_u32 s6, s84, 0x1000
	s_addc_u32 s7, s85, 0
	global_load_dword v118, v1, s[6:7]
	global_load_dword v119, v1, s[6:7] offset:2048
	s_mov_b32 s38, s28
	s_mov_b32 s39, s29
	global_load_dword v120, v1, s[38:39]
	global_load_dword v121, v1, s[38:39] offset:2048
	s_add_u32 s38, s38, 0x1000
	s_addc_u32 s39, s39, 0
	global_load_dword v122, v1, s[38:39]
	global_load_dword v123, v1, s[38:39] offset:2048
	s_add_u32 s38, s38, 0x1000
	s_addc_u32 s39, s39, 0
	global_load_dword v124, v1, s[38:39]
	global_load_dword v125, v1, s[38:39] offset:2048
	s_add_u32 s38, s38, 0x1000
	s_addc_u32 s39, s39, 0
	global_load_dword v126, v1, s[38:39]
	global_load_dword v127, v1, s[38:39] offset:2048
	s_add_u32 s38, s28, 0x3c000
	s_addc_u32 s39, s29, 0
	global_load_dword v128, v1, s[38:39]
	global_load_dword v129, v1, s[38:39] offset:2048
	s_add_u32 s38, s38, 0x1000
	s_addc_u32 s39, s39, 0
	global_load_dword v130, v1, s[38:39]
	global_load_dword v131, v1, s[38:39] offset:2048
	s_add_u32 s38, s38, 0x1000
	s_addc_u32 s39, s39, 0
	global_load_dword v132, v1, s[38:39]
	global_load_dword v133, v1, s[38:39] offset:2048
	s_add_u32 s38, s38, 0x1000
	s_addc_u32 s39, s39, 0
	global_load_dword v134, v1, s[38:39]
	global_load_dword v135, v1, s[38:39] offset:2048
	s_add_u32 s38, s28, 0x78000
	s_addc_u32 s39, s29, 0
	global_load_dword v136, v1, s[38:39]
	global_load_dword v137, v1, s[38:39] offset:2048
	s_add_u32 s38, s38, 0x1000
	s_addc_u32 s39, s39, 0
	global_load_dword v138, v1, s[38:39]
	global_load_dword v139, v1, s[38:39] offset:2048
	s_add_u32 s38, s38, 0x1000
	s_addc_u32 s39, s39, 0
	global_load_dword v140, v1, s[38:39]
	global_load_dword v141, v1, s[38:39] offset:2048
	s_add_u32 s38, s38, 0x1000
	s_addc_u32 s39, s39, 0
	global_load_dword v142, v1, s[38:39]
	global_load_dword v143, v1, s[38:39] offset:2048
	s_add_u32 s38, s28, 0xb4000
	s_addc_u32 s39, s29, 0
	global_load_dword v144, v1, s[38:39]
	global_load_dword v145, v1, s[38:39] offset:2048
	s_add_u32 s38, s38, 0x1000
	s_addc_u32 s39, s39, 0
	global_load_dword v146, v1, s[38:39]
	global_load_dword v147, v1, s[38:39] offset:2048
	s_add_u32 s38, s38, 0x1000
	s_addc_u32 s39, s39, 0
	global_load_dword v148, v1, s[38:39]
	global_load_dword v149, v1, s[38:39] offset:2048
	s_add_u32 s38, s38, 0x1000
	s_addc_u32 s39, s39, 0
	global_load_dword v150, v1, s[38:39]
	global_load_dword v151, v1, s[38:39] offset:2048
	s_add_u32 s38, s28, 0xf0000
	s_addc_u32 s39, s29, 0
	global_load_dword v152, v1, s[38:39]
	global_load_dword v153, v1, s[38:39] offset:2048
	s_add_u32 s38, s38, 0x1000
	s_addc_u32 s39, s39, 0
	global_load_dword v154, v1, s[38:39]
	global_load_dword v155, v1, s[38:39] offset:2048
	s_add_u32 s38, s38, 0x1000
	s_addc_u32 s39, s39, 0
	global_load_dword v156, v1, s[38:39]
	global_load_dword v157, v1, s[38:39] offset:2048
	s_add_u32 s38, s38, 0x1000
	s_addc_u32 s39, s39, 0
	global_load_dword v158, v1, s[38:39]
	global_load_dword v159, v1, s[38:39] offset:2048
	s_add_u32 s38, s28, 0x12c000
	s_addc_u32 s39, s29, 0
	global_load_dword v160, v1, s[38:39]
	global_load_dword v161, v1, s[38:39] offset:2048
	s_add_u32 s38, s38, 0x1000
	s_addc_u32 s39, s39, 0
	global_load_dword v162, v1, s[38:39]
	global_load_dword v163, v1, s[38:39] offset:2048
	s_add_u32 s38, s38, 0x1000
	s_addc_u32 s39, s39, 0
	global_load_dword v164, v1, s[38:39]
	global_load_dword v165, v1, s[38:39] offset:2048
	s_add_u32 s38, s38, 0x1000
	s_addc_u32 s39, s39, 0
	global_load_dword v166, v1, s[38:39]
	global_load_dword v167, v1, s[38:39] offset:2048
	s_add_u32 s38, s28, 0x168000
	s_addc_u32 s39, s29, 0
	global_load_dword v168, v1, s[38:39]
	global_load_dword v169, v1, s[38:39] offset:2048
	s_add_u32 s38, s38, 0x1000
	s_addc_u32 s39, s39, 0
	global_load_dword v170, v1, s[38:39]
	global_load_dword v171, v1, s[38:39] offset:2048
	s_add_u32 s38, s38, 0x1000
	s_addc_u32 s39, s39, 0
	global_load_dword v172, v1, s[38:39]
	global_load_dword v173, v1, s[38:39] offset:2048
	s_add_u32 s38, s38, 0x1000
	s_addc_u32 s39, s39, 0
	global_load_dword v174, v1, s[38:39]
	global_load_dword v175, v1, s[38:39] offset:2048
	s_add_u32 s38, s28, 0x1a4000
	s_addc_u32 s39, s29, 0
	global_load_dword v176, v1, s[38:39]
	global_load_dword v177, v1, s[38:39] offset:2048
	s_add_u32 s38, s38, 0x1000
	s_addc_u32 s39, s39, 0
	global_load_dword v178, v1, s[38:39]
	global_load_dword v179, v1, s[38:39] offset:2048
	s_add_u32 s38, s38, 0x1000
	s_addc_u32 s39, s39, 0
	global_load_dword v180, v1, s[38:39]
	global_load_dword v181, v1, s[38:39] offset:2048
	s_add_u32 s38, s38, 0x1000
	s_addc_u32 s39, s39, 0
	global_load_dword v182, v1, s[38:39]
	global_load_dword v183, v1, s[38:39] offset:2048
	s_waitcnt vmcnt(0)
; __global__ void __launch_bounds__(512, 2) fwd_kernel(KP p) {
;     ...
;         for (int e = tid; e < NSEQ * DM; e += 512) { const int s = e / DM, col = e % DM; float sh = p.in[I_BADA][col], sl = p.in[I_BADA][2048 + col];
; #pragma unroll
;             for (int ks = 0; ks < 8; ++ks) { sh += MODP[(size_t)(ks * 5 + s) * 12288 + col]; sl += MODP[(size_t)(ks * 5 + s) * 12288 + 2048 + col]; }
;             a1[e] = p.in[I_GMIX][col] * (1.f + sl); b1[e] = sh; }
	v_add_f32_e32 v3, v108, v120
	v_add_f32_e32 v4, v112, v124
	v_add_f32_e32 v3, v3, v128
	v_add_f32_e32 v4, v4, v132
	v_add_f32_e32 v3, v3, v136
	v_add_f32_e32 v4, v4, v140
	v_add_f32_e32 v3, v3, v144
	v_add_f32_e32 v4, v4, v148
	v_add_f32_e32 v3, v3, v152
	v_add_f32_e32 v4, v4, v156
	v_add_f32_e32 v3, v3, v160
	v_add_f32_e32 v4, v4, v164
	v_add_f32_e32 v3, v3, v168
	v_add_f32_e32 v4, v4, v172
	v_add_f32_e32 v3, v3, v176
	v_add_f32_e32 v4, v4, v180
	v_add_f32_e32 v4, 1.0, v4
	v_mul_f32_e32 v4, v116, v4
	ds_write_b32 v1, v4
	ds_write_b32 v2, v3
	v_add_f32_e32 v3, v109, v121
	v_add_f32_e32 v4, v113, v125
	v_add_f32_e32 v3, v3, v129
	v_add_f32_e32 v4, v4, v133
	v_add_f32_e32 v3, v3, v137
	v_add_f32_e32 v4, v4, v141
	v_add_f32_e32 v3, v3, v145
	v_add_f32_e32 v4, v4, v149
	v_add_f32_e32 v3, v3, v153
	v_add_f32_e32 v4, v4, v157
	v_add_f32_e32 v3, v3, v161
	v_add_f32_e32 v4, v4, v165
	v_add_f32_e32 v3, v3, v169
	v_add_f32_e32 v4, v4, v173
	v_add_f32_e32 v3, v3, v177
	v_add_f32_e32 v4, v4, v181
	v_add_f32_e32 v4, 1.0, v4
	v_mul_f32_e32 v4, v117, v4
	ds_write_b32 v1, v4 offset:2048
	ds_write_b32 v2, v3 offset:2048
	v_add_f32_e32 v3, v110, v122
	v_add_f32_e32 v4, v114, v126
	v_add_f32_e32 v3, v3, v130
	v_add_f32_e32 v4, v4, v134
	v_add_f32_e32 v3, v3, v138
	v_add_f32_e32 v4, v4, v142
	v_add_f32_e32 v3, v3, v146
	v_add_f32_e32 v4, v4, v150
	v_add_f32_e32 v3, v3, v154
	v_add_f32_e32 v4, v4, v158
	v_add_f32_e32 v3, v3, v162
	v_add_f32_e32 v4, v4, v166
	v_add_f32_e32 v3, v3, v170
	v_add_f32_e32 v4, v4, v174
	v_add_f32_e32 v3, v3, v178
	v_add_f32_e32 v4, v4, v182
	v_add_f32_e32 v4, 1.0, v4
	v_mul_f32_e32 v4, v118, v4
	ds_write_b32 v1, v4 offset:4096
	ds_write_b32 v2, v3 offset:4096
	v_add_f32_e32 v3, v111, v123
	v_add_f32_e32 v4, v115, v127
	v_add_f32_e32 v3, v3, v131
	v_add_f32_e32 v4, v4, v135
	v_add_f32_e32 v3, v3, v139
	v_add_f32_e32 v4, v4, v143
	v_add_f32_e32 v3, v3, v147
	v_add_f32_e32 v4, v4, v151
	v_add_f32_e32 v3, v3, v155
	v_add_f32_e32 v4, v4, v159
	v_add_f32_e32 v3, v3, v163
	v_add_f32_e32 v4, v4, v167
	v_add_f32_e32 v3, v3, v171
	v_add_f32_e32 v4, v4, v175
	v_add_f32_e32 v3, v3, v179
	v_add_f32_e32 v4, v4, v183
	v_add_f32_e32 v4, 1.0, v4
	v_mul_f32_e32 v4, v119, v4
	ds_write_b32 v1, v4 offset:6144
	ds_write_b32 v2, v3 offset:6144
	s_add_u32 s38, s28, 0xc000
	s_addc_u32 s39, s29, 0
	global_load_dword v120, v1, s[38:39]
	global_load_dword v121, v1, s[38:39] offset:2048
	s_add_u32 s38, s38, 0x1000
	s_addc_u32 s39, s39, 0
	global_load_dword v122, v1, s[38:39]
	global_load_dword v123, v1, s[38:39] offset:2048
	s_add_u32 s38, s38, 0x1000
	s_addc_u32 s39, s39, 0
	global_load_dword v124, v1, s[38:39]
	global_load_dword v125, v1, s[38:39] offset:2048
	s_add_u32 s38, s38, 0x1000
	s_addc_u32 s39, s39, 0
	global_load_dword v126, v1, s[38:39]
	global_load_dword v127, v1, s[38:39] offset:2048
	s_add_u32 s38, s28, 0x48000
	s_addc_u32 s39, s29, 0
	global_load_dword v128, v1, s[38:39]
	global_load_dword v129, v1, s[38:39] offset:2048
	s_add_u32 s38, s38, 0x1000
	s_addc_u32 s39, s39, 0
	global_load_dword v130, v1, s[38:39]
	global_load_dword v131, v1, s[38:39] offset:2048
	s_add_u32 s38, s38, 0x1000
	s_addc_u32 s39, s39, 0
	global_load_dword v132, v1, s[38:39]
	global_load_dword v133, v1, s[38:39] offset:2048
	s_add_u32 s38, s38, 0x1000
	s_addc_u32 s39, s39, 0
	global_load_dword v134, v1, s[38:39]
	global_load_dword v135, v1, s[38:39] offset:2048
	s_add_u32 s38, s28, 0x84000
	s_addc_u32 s39, s29, 0
	global_load_dword v136, v1, s[38:39]
	global_load_dword v137, v1, s[38:39] offset:2048
	s_add_u32 s38, s38, 0x1000
	s_addc_u32 s39, s39, 0
	global_load_dword v138, v1, s[38:39]
	global_load_dword v139, v1, s[38:39] offset:2048
	s_add_u32 s38, s38, 0x1000
	s_addc_u32 s39, s39, 0
	global_load_dword v140, v1, s[38:39]
	global_load_dword v141, v1, s[38:39] offset:2048
	s_add_u32 s38, s38, 0x1000
	s_addc_u32 s39, s39, 0
	global_load_dword v142, v1, s[38:39]
	global_load_dword v143, v1, s[38:39] offset:2048
	s_add_u32 s38, s28, 0xc0000
	s_addc_u32 s39, s29, 0
	global_load_dword v144, v1, s[38:39]
	global_load_dword v145, v1, s[38:39] offset:2048
	s_add_u32 s38, s38, 0x1000
	s_addc_u32 s39, s39, 0
	global_load_dword v146, v1, s[38:39]
	global_load_dword v147, v1, s[38:39] offset:2048
	s_add_u32 s38, s38, 0x1000
	s_addc_u32 s39, s39, 0
	global_load_dword v148, v1, s[38:39]
	global_load_dword v149, v1, s[38:39] offset:2048
	s_add_u32 s38, s38, 0x1000
	s_addc_u32 s39, s39, 0
	global_load_dword v150, v1, s[38:39]
	global_load_dword v151, v1, s[38:39] offset:2048
	s_add_u32 s38, s28, 0xfc000
	s_addc_u32 s39, s29, 0
	global_load_dword v152, v1, s[38:39]
	global_load_dword v153, v1, s[38:39] offset:2048
	s_add_u32 s38, s38, 0x1000
	s_addc_u32 s39, s39, 0
	global_load_dword v154, v1, s[38:39]
	global_load_dword v155, v1, s[38:39] offset:2048
	s_add_u32 s38, s38, 0x1000
	s_addc_u32 s39, s39, 0
	global_load_dword v156, v1, s[38:39]
	global_load_dword v157, v1, s[38:39] offset:2048
	s_add_u32 s38, s38, 0x1000
	s_addc_u32 s39, s39, 0
	global_load_dword v158, v1, s[38:39]
	global_load_dword v159, v1, s[38:39] offset:2048
	s_add_u32 s38, s28, 0x138000
	s_addc_u32 s39, s29, 0
	global_load_dword v160, v1, s[38:39]
	global_load_dword v161, v1, s[38:39] offset:2048
	s_add_u32 s38, s38, 0x1000
	s_addc_u32 s39, s39, 0
	global_load_dword v162, v1, s[38:39]
	global_load_dword v163, v1, s[38:39] offset:2048
	s_add_u32 s38, s38, 0x1000
	s_addc_u32 s39, s39, 0
	global_load_dword v164, v1, s[38:39]
	global_load_dword v165, v1, s[38:39] offset:2048
	s_add_u32 s38, s38, 0x1000
	s_addc_u32 s39, s39, 0
	global_load_dword v166, v1, s[38:39]
	global_load_dword v167, v1, s[38:39] offset:2048
	s_add_u32 s38, s28, 0x174000
	s_addc_u32 s39, s29, 0
	global_load_dword v168, v1, s[38:39]
	global_load_dword v169, v1, s[38:39] offset:2048
	s_add_u32 s38, s38, 0x1000
	s_addc_u32 s39, s39, 0
	global_load_dword v170, v1, s[38:39]
	global_load_dword v171, v1, s[38:39] offset:2048
	s_add_u32 s38, s38, 0x1000
	s_addc_u32 s39, s39, 0
	global_load_dword v172, v1, s[38:39]
	global_load_dword v173, v1, s[38:39] offset:2048
	s_add_u32 s38, s38, 0x1000
	s_addc_u32 s39, s39, 0
	global_load_dword v174, v1, s[38:39]
	global_load_dword v175, v1, s[38:39] offset:2048
	s_add_u32 s38, s28, 0x1b0000
	s_addc_u32 s39, s29, 0
	global_load_dword v176, v1, s[38:39]
	global_load_dword v177, v1, s[38:39] offset:2048
	s_add_u32 s38, s38, 0x1000
	s_addc_u32 s39, s39, 0
	global_load_dword v178, v1, s[38:39]
	global_load_dword v179, v1, s[38:39] offset:2048
	s_add_u32 s38, s38, 0x1000
	s_addc_u32 s39, s39, 0
	global_load_dword v180, v1, s[38:39]
	global_load_dword v181, v1, s[38:39] offset:2048
	s_add_u32 s38, s38, 0x1000
	s_addc_u32 s39, s39, 0
	global_load_dword v182, v1, s[38:39]
	global_load_dword v183, v1, s[38:39] offset:2048
	s_waitcnt vmcnt(0)
; __global__ void __launch_bounds__(512, 2) fwd_kernel(KP p) {
;     ...
;         for (int e = tid; e < NSEQ * DM; e += 512) { const int s = e / DM, col = e % DM; float sh = p.in[I_BADA][col], sl = p.in[I_BADA][2048 + col];
; #pragma unroll
;             for (int ks = 0; ks < 8; ++ks) { sh += MODP[(size_t)(ks * 5 + s) * 12288 + col]; sl += MODP[(size_t)(ks * 5 + s) * 12288 + 2048 + col]; }
;             a1[e] = p.in[I_GMIX][col] * (1.f + sl); b1[e] = sh; }
	v_add_f32_e32 v3, v108, v120
	v_add_f32_e32 v4, v112, v124
	v_add_f32_e32 v3, v3, v128
	v_add_f32_e32 v4, v4, v132
	v_add_f32_e32 v3, v3, v136
	v_add_f32_e32 v4, v4, v140
	v_add_f32_e32 v3, v3, v144
	v_add_f32_e32 v4, v4, v148
	v_add_f32_e32 v3, v3, v152
	v_add_f32_e32 v4, v4, v156
	v_add_f32_e32 v3, v3, v160
	v_add_f32_e32 v4, v4, v164
	v_add_f32_e32 v3, v3, v168
	v_add_f32_e32 v4, v4, v172
	v_add_f32_e32 v3, v3, v176
	v_add_f32_e32 v4, v4, v180
	v_add_f32_e32 v4, 1.0, v4
	v_mul_f32_e32 v4, v116, v4
	ds_write_b32 v1, v4 offset:8192
	ds_write_b32 v2, v3 offset:8192
	v_add_f32_e32 v3, v109, v121
	v_add_f32_e32 v4, v113, v125
	v_add_f32_e32 v3, v3, v129
	v_add_f32_e32 v4, v4, v133
	v_add_f32_e32 v3, v3, v137
	v_add_f32_e32 v4, v4, v141
	v_add_f32_e32 v3, v3, v145
	v_add_f32_e32 v4, v4, v149
	v_add_f32_e32 v3, v3, v153
	v_add_f32_e32 v4, v4, v157
	v_add_f32_e32 v3, v3, v161
	v_add_f32_e32 v4, v4, v165
	v_add_f32_e32 v3, v3, v169
	v_add_f32_e32 v4, v4, v173
	v_add_f32_e32 v3, v3, v177
	v_add_f32_e32 v4, v4, v181
	v_add_f32_e32 v4, 1.0, v4
	v_mul_f32_e32 v4, v117, v4
	ds_write_b32 v1, v4 offset:10240
	ds_write_b32 v2, v3 offset:10240
	v_add_f32_e32 v3, v110, v122
	v_add_f32_e32 v4, v114, v126
	v_add_f32_e32 v3, v3, v130
	v_add_f32_e32 v4, v4, v134
	v_add_f32_e32 v3, v3, v138
	v_add_f32_e32 v4, v4, v142
	v_add_f32_e32 v3, v3, v146
	v_add_f32_e32 v4, v4, v150
	v_add_f32_e32 v3, v3, v154
	v_add_f32_e32 v4, v4, v158
	v_add_f32_e32 v3, v3, v162
	v_add_f32_e32 v4, v4, v166
	v_add_f32_e32 v3, v3, v170
	v_add_f32_e32 v4, v4, v174
	v_add_f32_e32 v3, v3, v178
	v_add_f32_e32 v4, v4, v182
	v_add_f32_e32 v4, 1.0, v4
	v_mul_f32_e32 v4, v118, v4
	ds_write_b32 v1, v4 offset:12288
	ds_write_b32 v2, v3 offset:12288
	v_add_f32_e32 v3, v111, v123
	v_add_f32_e32 v4, v115, v127
	v_add_f32_e32 v3, v3, v131
	v_add_f32_e32 v4, v4, v135
	v_add_f32_e32 v3, v3, v139
	v_add_f32_e32 v4, v4, v143
	v_add_f32_e32 v3, v3, v147
	v_add_f32_e32 v4, v4, v151
	v_add_f32_e32 v3, v3, v155
	v_add_f32_e32 v4, v4, v159
	v_add_f32_e32 v3, v3, v163
	v_add_f32_e32 v4, v4, v167
	v_add_f32_e32 v3, v3, v171
	v_add_f32_e32 v4, v4, v175
	v_add_f32_e32 v3, v3, v179
	v_add_f32_e32 v4, v4, v183
	v_add_f32_e32 v4, 1.0, v4
	v_mul_f32_e32 v4, v119, v4
	ds_write_b32 v1, v4 offset:14336
	ds_write_b32 v2, v3 offset:14336
	s_add_u32 s38, s28, 0x18000
	s_addc_u32 s39, s29, 0
	global_load_dword v120, v1, s[38:39]
	global_load_dword v121, v1, s[38:39] offset:2048
	s_add_u32 s38, s38, 0x1000
	s_addc_u32 s39, s39, 0
	global_load_dword v122, v1, s[38:39]
	global_load_dword v123, v1, s[38:39] offset:2048
	s_add_u32 s38, s38, 0x1000
	s_addc_u32 s39, s39, 0
	global_load_dword v124, v1, s[38:39]
	global_load_dword v125, v1, s[38:39] offset:2048
	s_add_u32 s38, s38, 0x1000
	s_addc_u32 s39, s39, 0
	global_load_dword v126, v1, s[38:39]
	global_load_dword v127, v1, s[38:39] offset:2048
	s_add_u32 s38, s28, 0x54000
	s_addc_u32 s39, s29, 0
	global_load_dword v128, v1, s[38:39]
	global_load_dword v129, v1, s[38:39] offset:2048
	s_add_u32 s38, s38, 0x1000
	s_addc_u32 s39, s39, 0
	global_load_dword v130, v1, s[38:39]
	global_load_dword v131, v1, s[38:39] offset:2048
	s_add_u32 s38, s38, 0x1000
	s_addc_u32 s39, s39, 0
	global_load_dword v132, v1, s[38:39]
	global_load_dword v133, v1, s[38:39] offset:2048
	s_add_u32 s38, s38, 0x1000
	s_addc_u32 s39, s39, 0
	global_load_dword v134, v1, s[38:39]
	global_load_dword v135, v1, s[38:39] offset:2048
	s_add_u32 s38, s28, 0x90000
	s_addc_u32 s39, s29, 0
	global_load_dword v136, v1, s[38:39]
	global_load_dword v137, v1, s[38:39] offset:2048
	s_add_u32 s38, s38, 0x1000
	s_addc_u32 s39, s39, 0
	global_load_dword v138, v1, s[38:39]
	global_load_dword v139, v1, s[38:39] offset:2048
	s_add_u32 s38, s38, 0x1000
	s_addc_u32 s39, s39, 0
	global_load_dword v140, v1, s[38:39]
	global_load_dword v141, v1, s[38:39] offset:2048
	s_add_u32 s38, s38, 0x1000
	s_addc_u32 s39, s39, 0
	global_load_dword v142, v1, s[38:39]
	global_load_dword v143, v1, s[38:39] offset:2048
	s_add_u32 s38, s28, 0xcc000
	s_addc_u32 s39, s29, 0
	global_load_dword v144, v1, s[38:39]
	global_load_dword v145, v1, s[38:39] offset:2048
	s_add_u32 s38, s38, 0x1000
	s_addc_u32 s39, s39, 0
	global_load_dword v146, v1, s[38:39]
	global_load_dword v147, v1, s[38:39] offset:2048
	s_add_u32 s38, s38, 0x1000
	s_addc_u32 s39, s39, 0
	global_load_dword v148, v1, s[38:39]
	global_load_dword v149, v1, s[38:39] offset:2048
	s_add_u32 s38, s38, 0x1000
	s_addc_u32 s39, s39, 0
	global_load_dword v150, v1, s[38:39]
	global_load_dword v151, v1, s[38:39] offset:2048
	s_add_u32 s38, s28, 0x108000
	s_addc_u32 s39, s29, 0
	global_load_dword v152, v1, s[38:39]
	global_load_dword v153, v1, s[38:39] offset:2048
	s_add_u32 s38, s38, 0x1000
	s_addc_u32 s39, s39, 0
	global_load_dword v154, v1, s[38:39]
	global_load_dword v155, v1, s[38:39] offset:2048
	s_add_u32 s38, s38, 0x1000
	s_addc_u32 s39, s39, 0
	global_load_dword v156, v1, s[38:39]
	global_load_dword v157, v1, s[38:39] offset:2048
	s_add_u32 s38, s38, 0x1000
	s_addc_u32 s39, s39, 0
	global_load_dword v158, v1, s[38:39]
	global_load_dword v159, v1, s[38:39] offset:2048
	s_add_u32 s38, s28, 0x144000
	s_addc_u32 s39, s29, 0
	global_load_dword v160, v1, s[38:39]
	global_load_dword v161, v1, s[38:39] offset:2048
	s_add_u32 s38, s38, 0x1000
	s_addc_u32 s39, s39, 0
	global_load_dword v162, v1, s[38:39]
	global_load_dword v163, v1, s[38:39] offset:2048
	s_add_u32 s38, s38, 0x1000
	s_addc_u32 s39, s39, 0
	global_load_dword v164, v1, s[38:39]
	global_load_dword v165, v1, s[38:39] offset:2048
	s_add_u32 s38, s38, 0x1000
	s_addc_u32 s39, s39, 0
	global_load_dword v166, v1, s[38:39]
	global_load_dword v167, v1, s[38:39] offset:2048
	s_add_u32 s38, s28, 0x180000
	s_addc_u32 s39, s29, 0
	global_load_dword v168, v1, s[38:39]
	global_load_dword v169, v1, s[38:39] offset:2048
	s_add_u32 s38, s38, 0x1000
	s_addc_u32 s39, s39, 0
	global_load_dword v170, v1, s[38:39]
	global_load_dword v171, v1, s[38:39] offset:2048
	s_add_u32 s38, s38, 0x1000
	s_addc_u32 s39, s39, 0
	global_load_dword v172, v1, s[38:39]
	global_load_dword v173, v1, s[38:39] offset:2048
	s_add_u32 s38, s38, 0x1000
	s_addc_u32 s39, s39, 0
	global_load_dword v174, v1, s[38:39]
	global_load_dword v175, v1, s[38:39] offset:2048
	s_add_u32 s38, s28, 0x1bc000
	s_addc_u32 s39, s29, 0
	global_load_dword v176, v1, s[38:39]
	global_load_dword v177, v1, s[38:39] offset:2048
	s_add_u32 s38, s38, 0x1000
	s_addc_u32 s39, s39, 0
	global_load_dword v178, v1, s[38:39]
	global_load_dword v179, v1, s[38:39] offset:2048
	s_add_u32 s38, s38, 0x1000
	s_addc_u32 s39, s39, 0
	global_load_dword v180, v1, s[38:39]
	global_load_dword v181, v1, s[38:39] offset:2048
	s_add_u32 s38, s38, 0x1000
	s_addc_u32 s39, s39, 0
	global_load_dword v182, v1, s[38:39]
	global_load_dword v183, v1, s[38:39] offset:2048
	s_waitcnt vmcnt(0)
; __global__ void __launch_bounds__(512, 2) fwd_kernel(KP p) {
;     ...
;         for (int e = tid; e < NSEQ * DM; e += 512) { const int s = e / DM, col = e % DM; float sh = p.in[I_BADA][col], sl = p.in[I_BADA][2048 + col];
; #pragma unroll
;             for (int ks = 0; ks < 8; ++ks) { sh += MODP[(size_t)(ks * 5 + s) * 12288 + col]; sl += MODP[(size_t)(ks * 5 + s) * 12288 + 2048 + col]; }
;             a1[e] = p.in[I_GMIX][col] * (1.f + sl); b1[e] = sh; }
	v_add_f32_e32 v3, v108, v120
	v_add_f32_e32 v4, v112, v124
	v_add_f32_e32 v3, v3, v128
	v_add_f32_e32 v4, v4, v132
	v_add_f32_e32 v3, v3, v136
	v_add_f32_e32 v4, v4, v140
	v_add_f32_e32 v3, v3, v144
	v_add_f32_e32 v4, v4, v148
	v_add_f32_e32 v3, v3, v152
	v_add_f32_e32 v4, v4, v156
	v_add_f32_e32 v3, v3, v160
	v_add_f32_e32 v4, v4, v164
	v_add_f32_e32 v3, v3, v168
	v_add_f32_e32 v4, v4, v172
	v_add_f32_e32 v3, v3, v176
	v_add_f32_e32 v4, v4, v180
	v_add_f32_e32 v4, 1.0, v4
	v_mul_f32_e32 v4, v116, v4
	ds_write_b32 v1, v4 offset:16384
	ds_write_b32 v2, v3 offset:16384
	v_add_f32_e32 v3, v109, v121
	v_add_f32_e32 v4, v113, v125
	v_add_f32_e32 v3, v3, v129
	v_add_f32_e32 v4, v4, v133
	v_add_f32_e32 v3, v3, v137
	v_add_f32_e32 v4, v4, v141
	v_add_f32_e32 v3, v3, v145
	v_add_f32_e32 v4, v4, v149
	v_add_f32_e32 v3, v3, v153
	v_add_f32_e32 v4, v4, v157
	v_add_f32_e32 v3, v3, v161
	v_add_f32_e32 v4, v4, v165
	v_add_f32_e32 v3, v3, v169
	v_add_f32_e32 v4, v4, v173
	v_add_f32_e32 v3, v3, v177
	v_add_f32_e32 v4, v4, v181
	v_add_f32_e32 v4, 1.0, v4
	v_mul_f32_e32 v4, v117, v4
	ds_write_b32 v1, v4 offset:18432
	ds_write_b32 v2, v3 offset:18432
	v_add_f32_e32 v3, v110, v122
	v_add_f32_e32 v4, v114, v126
	v_add_f32_e32 v3, v3, v130
	v_add_f32_e32 v4, v4, v134
	v_add_f32_e32 v3, v3, v138
	v_add_f32_e32 v4, v4, v142
	v_add_f32_e32 v3, v3, v146
	v_add_f32_e32 v4, v4, v150
	v_add_f32_e32 v3, v3, v154
	v_add_f32_e32 v4, v4, v158
	v_add_f32_e32 v3, v3, v162
	v_add_f32_e32 v4, v4, v166
	v_add_f32_e32 v3, v3, v170
	v_add_f32_e32 v4, v4, v174
	v_add_f32_e32 v3, v3, v178
	v_add_f32_e32 v4, v4, v182
	v_add_f32_e32 v4, 1.0, v4
	v_mul_f32_e32 v4, v118, v4
	ds_write_b32 v1, v4 offset:20480
	ds_write_b32 v2, v3 offset:20480
	v_add_f32_e32 v3, v111, v123
	v_add_f32_e32 v4, v115, v127
	v_add_f32_e32 v3, v3, v131
	v_add_f32_e32 v4, v4, v135
	v_add_f32_e32 v3, v3, v139
	v_add_f32_e32 v4, v4, v143
	v_add_f32_e32 v3, v3, v147
	v_add_f32_e32 v4, v4, v151
	v_add_f32_e32 v3, v3, v155
	v_add_f32_e32 v4, v4, v159
	v_add_f32_e32 v3, v3, v163
	v_add_f32_e32 v4, v4, v167
	v_add_f32_e32 v3, v3, v171
	v_add_f32_e32 v4, v4, v175
	v_add_f32_e32 v3, v3, v179
	v_add_f32_e32 v4, v4, v183
	v_add_f32_e32 v4, 1.0, v4
	v_mul_f32_e32 v4, v119, v4
	ds_write_b32 v1, v4 offset:22528
	ds_write_b32 v2, v3 offset:22528
	s_add_u32 s38, s28, 0x24000
	s_addc_u32 s39, s29, 0
	global_load_dword v120, v1, s[38:39]
	global_load_dword v121, v1, s[38:39] offset:2048
	s_add_u32 s38, s38, 0x1000
	s_addc_u32 s39, s39, 0
	global_load_dword v122, v1, s[38:39]
	global_load_dword v123, v1, s[38:39] offset:2048
	s_add_u32 s38, s38, 0x1000
	s_addc_u32 s39, s39, 0
	global_load_dword v124, v1, s[38:39]
	global_load_dword v125, v1, s[38:39] offset:2048
	s_add_u32 s38, s38, 0x1000
	s_addc_u32 s39, s39, 0
	global_load_dword v126, v1, s[38:39]
	global_load_dword v127, v1, s[38:39] offset:2048
	s_add_u32 s38, s28, 0x60000
	s_addc_u32 s39, s29, 0
	global_load_dword v128, v1, s[38:39]
	global_load_dword v129, v1, s[38:39] offset:2048
	s_add_u32 s38, s38, 0x1000
	s_addc_u32 s39, s39, 0
	global_load_dword v130, v1, s[38:39]
	global_load_dword v131, v1, s[38:39] offset:2048
	s_add_u32 s38, s38, 0x1000
	s_addc_u32 s39, s39, 0
	global_load_dword v132, v1, s[38:39]
	global_load_dword v133, v1, s[38:39] offset:2048
	s_add_u32 s38, s38, 0x1000
	s_addc_u32 s39, s39, 0
	global_load_dword v134, v1, s[38:39]
	global_load_dword v135, v1, s[38:39] offset:2048
	s_add_u32 s38, s28, 0x9c000
	s_addc_u32 s39, s29, 0
	global_load_dword v136, v1, s[38:39]
	global_load_dword v137, v1, s[38:39] offset:2048
	s_add_u32 s38, s38, 0x1000
	s_addc_u32 s39, s39, 0
	global_load_dword v138, v1, s[38:39]
	global_load_dword v139, v1, s[38:39] offset:2048
	s_add_u32 s38, s38, 0x1000
	s_addc_u32 s39, s39, 0
	global_load_dword v140, v1, s[38:39]
	global_load_dword v141, v1, s[38:39] offset:2048
	s_add_u32 s38, s38, 0x1000
	s_addc_u32 s39, s39, 0
	global_load_dword v142, v1, s[38:39]
	global_load_dword v143, v1, s[38:39] offset:2048
	s_add_u32 s38, s28, 0xd8000
	s_addc_u32 s39, s29, 0
	global_load_dword v144, v1, s[38:39]
	global_load_dword v145, v1, s[38:39] offset:2048
	s_add_u32 s38, s38, 0x1000
	s_addc_u32 s39, s39, 0
	global_load_dword v146, v1, s[38:39]
	global_load_dword v147, v1, s[38:39] offset:2048
	s_add_u32 s38, s38, 0x1000
	s_addc_u32 s39, s39, 0
	global_load_dword v148, v1, s[38:39]
	global_load_dword v149, v1, s[38:39] offset:2048
	s_add_u32 s38, s38, 0x1000
	s_addc_u32 s39, s39, 0
	global_load_dword v150, v1, s[38:39]
	global_load_dword v151, v1, s[38:39] offset:2048
	s_add_u32 s38, s28, 0x114000
	s_addc_u32 s39, s29, 0
	global_load_dword v152, v1, s[38:39]
	global_load_dword v153, v1, s[38:39] offset:2048
	s_add_u32 s38, s38, 0x1000
	s_addc_u32 s39, s39, 0
	global_load_dword v154, v1, s[38:39]
	global_load_dword v155, v1, s[38:39] offset:2048
	s_add_u32 s38, s38, 0x1000
	s_addc_u32 s39, s39, 0
	global_load_dword v156, v1, s[38:39]
	global_load_dword v157, v1, s[38:39] offset:2048
	s_add_u32 s38, s38, 0x1000
	s_addc_u32 s39, s39, 0
	global_load_dword v158, v1, s[38:39]
	global_load_dword v159, v1, s[38:39] offset:2048
	s_add_u32 s38, s28, 0x150000
	s_addc_u32 s39, s29, 0
	global_load_dword v160, v1, s[38:39]
	global_load_dword v161, v1, s[38:39] offset:2048
	s_add_u32 s38, s38, 0x1000
	s_addc_u32 s39, s39, 0
	global_load_dword v162, v1, s[38:39]
	global_load_dword v163, v1, s[38:39] offset:2048
	s_add_u32 s38, s38, 0x1000
	s_addc_u32 s39, s39, 0
	global_load_dword v164, v1, s[38:39]
	global_load_dword v165, v1, s[38:39] offset:2048
	s_add_u32 s38, s38, 0x1000
	s_addc_u32 s39, s39, 0
	global_load_dword v166, v1, s[38:39]
	global_load_dword v167, v1, s[38:39] offset:2048
	s_add_u32 s38, s28, 0x18c000
	s_addc_u32 s39, s29, 0
	global_load_dword v168, v1, s[38:39]
	global_load_dword v169, v1, s[38:39] offset:2048
	s_add_u32 s38, s38, 0x1000
	s_addc_u32 s39, s39, 0
	global_load_dword v170, v1, s[38:39]
	global_load_dword v171, v1, s[38:39] offset:2048
	s_add_u32 s38, s38, 0x1000
	s_addc_u32 s39, s39, 0
	global_load_dword v172, v1, s[38:39]
	global_load_dword v173, v1, s[38:39] offset:2048
	s_add_u32 s38, s38, 0x1000
	s_addc_u32 s39, s39, 0
	global_load_dword v174, v1, s[38:39]
	global_load_dword v175, v1, s[38:39] offset:2048
	s_add_u32 s38, s28, 0x1c8000
	s_addc_u32 s39, s29, 0
	global_load_dword v176, v1, s[38:39]
	global_load_dword v177, v1, s[38:39] offset:2048
	s_add_u32 s38, s38, 0x1000
	s_addc_u32 s39, s39, 0
	global_load_dword v178, v1, s[38:39]
	global_load_dword v179, v1, s[38:39] offset:2048
	s_add_u32 s38, s38, 0x1000
	s_addc_u32 s39, s39, 0
	global_load_dword v180, v1, s[38:39]
	global_load_dword v181, v1, s[38:39] offset:2048
	s_add_u32 s38, s38, 0x1000
	s_addc_u32 s39, s39, 0
	global_load_dword v182, v1, s[38:39]
	global_load_dword v183, v1, s[38:39] offset:2048
	s_waitcnt vmcnt(0)
; __global__ void __launch_bounds__(512, 2) fwd_kernel(KP p) {
;     ...
;         for (int e = tid; e < NSEQ * DM; e += 512) { const int s = e / DM, col = e % DM; float sh = p.in[I_BADA][col], sl = p.in[I_BADA][2048 + col];
; #pragma unroll
;             for (int ks = 0; ks < 8; ++ks) { sh += MODP[(size_t)(ks * 5 + s) * 12288 + col]; sl += MODP[(size_t)(ks * 5 + s) * 12288 + 2048 + col]; }
;             a1[e] = p.in[I_GMIX][col] * (1.f + sl); b1[e] = sh; }
	v_add_f32_e32 v3, v108, v120
	v_add_f32_e32 v4, v112, v124
	v_add_f32_e32 v3, v3, v128
	v_add_f32_e32 v4, v4, v132
	v_add_f32_e32 v3, v3, v136
	v_add_f32_e32 v4, v4, v140
	v_add_f32_e32 v3, v3, v144
	v_add_f32_e32 v4, v4, v148
	v_add_f32_e32 v3, v3, v152
	v_add_f32_e32 v4, v4, v156
	v_add_f32_e32 v3, v3, v160
	v_add_f32_e32 v4, v4, v164
	v_add_f32_e32 v3, v3, v168
	v_add_f32_e32 v4, v4, v172
	v_add_f32_e32 v3, v3, v176
	v_add_f32_e32 v4, v4, v180
	v_add_f32_e32 v4, 1.0, v4
	v_mul_f32_e32 v4, v116, v4
	ds_write_b32 v1, v4 offset:24576
	ds_write_b32 v2, v3 offset:24576
	v_add_f32_e32 v3, v109, v121
	v_add_f32_e32 v4, v113, v125
	v_add_f32_e32 v3, v3, v129
	v_add_f32_e32 v4, v4, v133
	v_add_f32_e32 v3, v3, v137
	v_add_f32_e32 v4, v4, v141
	v_add_f32_e32 v3, v3, v145
	v_add_f32_e32 v4, v4, v149
	v_add_f32_e32 v3, v3, v153
	v_add_f32_e32 v4, v4, v157
	v_add_f32_e32 v3, v3, v161
	v_add_f32_e32 v4, v4, v165
	v_add_f32_e32 v3, v3, v169
	v_add_f32_e32 v4, v4, v173
	v_add_f32_e32 v3, v3, v177
	v_add_f32_e32 v4, v4, v181
	v_add_f32_e32 v4, 1.0, v4
	v_mul_f32_e32 v4, v117, v4
	ds_write_b32 v1, v4 offset:26624
	ds_write_b32 v2, v3 offset:26624
	v_add_f32_e32 v3, v110, v122
	v_add_f32_e32 v4, v114, v126
	v_add_f32_e32 v3, v3, v130
	v_add_f32_e32 v4, v4, v134
	v_add_f32_e32 v3, v3, v138
	v_add_f32_e32 v4, v4, v142
	v_add_f32_e32 v3, v3, v146
	v_add_f32_e32 v4, v4, v150
	v_add_f32_e32 v3, v3, v154
	v_add_f32_e32 v4, v4, v158
	v_add_f32_e32 v3, v3, v162
	v_add_f32_e32 v4, v4, v166
	v_add_f32_e32 v3, v3, v170
	v_add_f32_e32 v4, v4, v174
	v_add_f32_e32 v3, v3, v178
	v_add_f32_e32 v4, v4, v182
	v_add_f32_e32 v4, 1.0, v4
	v_mul_f32_e32 v4, v118, v4
	ds_write_b32 v1, v4 offset:28672
	ds_write_b32 v2, v3 offset:28672
	v_add_f32_e32 v3, v111, v123
	v_add_f32_e32 v4, v115, v127
	v_add_f32_e32 v3, v3, v131
	v_add_f32_e32 v4, v4, v135
	v_add_f32_e32 v3, v3, v139
	v_add_f32_e32 v4, v4, v143
	v_add_f32_e32 v3, v3, v147
	v_add_f32_e32 v4, v4, v151
	v_add_f32_e32 v3, v3, v155
	v_add_f32_e32 v4, v4, v159
	v_add_f32_e32 v3, v3, v163
	v_add_f32_e32 v4, v4, v167
	v_add_f32_e32 v3, v3, v171
	v_add_f32_e32 v4, v4, v175
	v_add_f32_e32 v3, v3, v179
	v_add_f32_e32 v4, v4, v183
	v_add_f32_e32 v4, 1.0, v4
	v_mul_f32_e32 v4, v119, v4
	ds_write_b32 v1, v4 offset:30720
	ds_write_b32 v2, v3 offset:30720
	s_add_u32 s38, s28, 0x30000
	s_addc_u32 s39, s29, 0
	global_load_dword v120, v1, s[38:39]
	global_load_dword v121, v1, s[38:39] offset:2048
	s_add_u32 s38, s38, 0x1000
	s_addc_u32 s39, s39, 0
	global_load_dword v122, v1, s[38:39]
	global_load_dword v123, v1, s[38:39] offset:2048
	s_add_u32 s38, s38, 0x1000
	s_addc_u32 s39, s39, 0
	global_load_dword v124, v1, s[38:39]
	global_load_dword v125, v1, s[38:39] offset:2048
	s_add_u32 s38, s38, 0x1000
	s_addc_u32 s39, s39, 0
	global_load_dword v126, v1, s[38:39]
	global_load_dword v127, v1, s[38:39] offset:2048
	s_add_u32 s38, s28, 0x6c000
	s_addc_u32 s39, s29, 0
	global_load_dword v128, v1, s[38:39]
	global_load_dword v129, v1, s[38:39] offset:2048
	s_add_u32 s38, s38, 0x1000
	s_addc_u32 s39, s39, 0
	global_load_dword v130, v1, s[38:39]
	global_load_dword v131, v1, s[38:39] offset:2048
	s_add_u32 s38, s38, 0x1000
	s_addc_u32 s39, s39, 0
	global_load_dword v132, v1, s[38:39]
	global_load_dword v133, v1, s[38:39] offset:2048
	s_add_u32 s38, s38, 0x1000
	s_addc_u32 s39, s39, 0
	global_load_dword v134, v1, s[38:39]
	global_load_dword v135, v1, s[38:39] offset:2048
	s_add_u32 s38, s28, 0xa8000
	s_addc_u32 s39, s29, 0
	global_load_dword v136, v1, s[38:39]
	global_load_dword v137, v1, s[38:39] offset:2048
	s_add_u32 s38, s38, 0x1000
	s_addc_u32 s39, s39, 0
	global_load_dword v138, v1, s[38:39]
	global_load_dword v139, v1, s[38:39] offset:2048
	s_add_u32 s38, s38, 0x1000
	s_addc_u32 s39, s39, 0
	global_load_dword v140, v1, s[38:39]
	global_load_dword v141, v1, s[38:39] offset:2048
	s_add_u32 s38, s38, 0x1000
	s_addc_u32 s39, s39, 0
	global_load_dword v142, v1, s[38:39]
	global_load_dword v143, v1, s[38:39] offset:2048
	s_add_u32 s38, s28, 0xe4000
	s_addc_u32 s39, s29, 0
	global_load_dword v144, v1, s[38:39]
	global_load_dword v145, v1, s[38:39] offset:2048
	s_add_u32 s38, s38, 0x1000
	s_addc_u32 s39, s39, 0
	global_load_dword v146, v1, s[38:39]
	global_load_dword v147, v1, s[38:39] offset:2048
	s_add_u32 s38, s38, 0x1000
	s_addc_u32 s39, s39, 0
	global_load_dword v148, v1, s[38:39]
	global_load_dword v149, v1, s[38:39] offset:2048
	s_add_u32 s38, s38, 0x1000
	s_addc_u32 s39, s39, 0
	global_load_dword v150, v1, s[38:39]
	global_load_dword v151, v1, s[38:39] offset:2048
	s_add_u32 s38, s28, 0x120000
	s_addc_u32 s39, s29, 0
	global_load_dword v152, v1, s[38:39]
	global_load_dword v153, v1, s[38:39] offset:2048
	s_add_u32 s38, s38, 0x1000
	s_addc_u32 s39, s39, 0
	global_load_dword v154, v1, s[38:39]
	global_load_dword v155, v1, s[38:39] offset:2048
	s_add_u32 s38, s38, 0x1000
	s_addc_u32 s39, s39, 0
	global_load_dword v156, v1, s[38:39]
	global_load_dword v157, v1, s[38:39] offset:2048
	s_add_u32 s38, s38, 0x1000
	s_addc_u32 s39, s39, 0
	global_load_dword v158, v1, s[38:39]
	global_load_dword v159, v1, s[38:39] offset:2048
	s_add_u32 s38, s28, 0x15c000
	s_addc_u32 s39, s29, 0
	global_load_dword v160, v1, s[38:39]
	global_load_dword v161, v1, s[38:39] offset:2048
	s_add_u32 s38, s38, 0x1000
	s_addc_u32 s39, s39, 0
	global_load_dword v162, v1, s[38:39]
	global_load_dword v163, v1, s[38:39] offset:2048
	s_add_u32 s38, s38, 0x1000
	s_addc_u32 s39, s39, 0
	global_load_dword v164, v1, s[38:39]
	global_load_dword v165, v1, s[38:39] offset:2048
	s_add_u32 s38, s38, 0x1000
	s_addc_u32 s39, s39, 0
	global_load_dword v166, v1, s[38:39]
	global_load_dword v167, v1, s[38:39] offset:2048
	s_add_u32 s38, s28, 0x198000
	s_addc_u32 s39, s29, 0
	global_load_dword v168, v1, s[38:39]
	global_load_dword v169, v1, s[38:39] offset:2048
	s_add_u32 s38, s38, 0x1000
	s_addc_u32 s39, s39, 0
	global_load_dword v170, v1, s[38:39]
	global_load_dword v171, v1, s[38:39] offset:2048
	s_add_u32 s38, s38, 0x1000
	s_addc_u32 s39, s39, 0
	global_load_dword v172, v1, s[38:39]
	global_load_dword v173, v1, s[38:39] offset:2048
	s_add_u32 s38, s38, 0x1000
	s_addc_u32 s39, s39, 0
	global_load_dword v174, v1, s[38:39]
	global_load_dword v175, v1, s[38:39] offset:2048
	s_add_u32 s38, s28, 0x1d4000
	s_addc_u32 s39, s29, 0
	global_load_dword v176, v1, s[38:39]
	global_load_dword v177, v1, s[38:39] offset:2048
	s_add_u32 s38, s38, 0x1000
	s_addc_u32 s39, s39, 0
	global_load_dword v178, v1, s[38:39]
	global_load_dword v179, v1, s[38:39] offset:2048
	s_add_u32 s38, s38, 0x1000
	s_addc_u32 s39, s39, 0
	global_load_dword v180, v1, s[38:39]
	global_load_dword v181, v1, s[38:39] offset:2048
	s_add_u32 s38, s38, 0x1000
	s_addc_u32 s39, s39, 0
	global_load_dword v182, v1, s[38:39]
	global_load_dword v183, v1, s[38:39] offset:2048
	s_waitcnt vmcnt(0)
; __global__ void __launch_bounds__(512, 2) fwd_kernel(KP p) {
;     ...
;         for (int e = tid; e < NSEQ * DM; e += 512) { const int s = e / DM, col = e % DM; float sh = p.in[I_BADA][col], sl = p.in[I_BADA][2048 + col];
; #pragma unroll
;             for (int ks = 0; ks < 8; ++ks) { sh += MODP[(size_t)(ks * 5 + s) * 12288 + col]; sl += MODP[(size_t)(ks * 5 + s) * 12288 + 2048 + col]; }
;             a1[e] = p.in[I_GMIX][col] * (1.f + sl); b1[e] = sh; }
	v_add_f32_e32 v3, v108, v120
	v_add_f32_e32 v4, v112, v124
	v_add_f32_e32 v3, v3, v128
	v_add_f32_e32 v4, v4, v132
	v_add_f32_e32 v3, v3, v136
	v_add_f32_e32 v4, v4, v140
	v_add_f32_e32 v3, v3, v144
	v_add_f32_e32 v4, v4, v148
	v_add_f32_e32 v3, v3, v152
	v_add_f32_e32 v4, v4, v156
	v_add_f32_e32 v3, v3, v160
	v_add_f32_e32 v4, v4, v164
	v_add_f32_e32 v3, v3, v168
	v_add_f32_e32 v4, v4, v172
	v_add_f32_e32 v3, v3, v176
	v_add_f32_e32 v4, v4, v180
	v_add_f32_e32 v4, 1.0, v4
	v_mul_f32_e32 v4, v116, v4
	ds_write_b32 v1, v4 offset:32768
	ds_write_b32 v2, v3 offset:32768
	v_add_f32_e32 v3, v109, v121
	v_add_f32_e32 v4, v113, v125
	v_add_f32_e32 v3, v3, v129
	v_add_f32_e32 v4, v4, v133
	v_add_f32_e32 v3, v3, v137
	v_add_f32_e32 v4, v4, v141
	v_add_f32_e32 v3, v3, v145
	v_add_f32_e32 v4, v4, v149
	v_add_f32_e32 v3, v3, v153
	v_add_f32_e32 v4, v4, v157
	v_add_f32_e32 v3, v3, v161
	v_add_f32_e32 v4, v4, v165
	v_add_f32_e32 v3, v3, v169
	v_add_f32_e32 v4, v4, v173
	v_add_f32_e32 v3, v3, v177
	v_add_f32_e32 v4, v4, v181
	v_add_f32_e32 v4, 1.0, v4
	v_mul_f32_e32 v4, v117, v4
	ds_write_b32 v1, v4 offset:34816
	ds_write_b32 v2, v3 offset:34816
	v_add_f32_e32 v3, v110, v122
	v_add_f32_e32 v4, v114, v126
	v_add_f32_e32 v3, v3, v130
	v_add_f32_e32 v4, v4, v134
	v_add_f32_e32 v3, v3, v138
	v_add_f32_e32 v4, v4, v142
	v_add_f32_e32 v3, v3, v146
	v_add_f32_e32 v4, v4, v150
	v_add_f32_e32 v3, v3, v154
	v_add_f32_e32 v4, v4, v158
	v_add_f32_e32 v3, v3, v162
	v_add_f32_e32 v4, v4, v166
	v_add_f32_e32 v3, v3, v170
	v_add_f32_e32 v4, v4, v174
	v_add_f32_e32 v3, v3, v178
	v_add_f32_e32 v4, v4, v182
	v_add_f32_e32 v4, 1.0, v4
	v_mul_f32_e32 v4, v118, v4
	ds_write_b32 v1, v4 offset:36864
	ds_write_b32 v2, v3 offset:36864
	v_add_f32_e32 v3, v111, v123
	v_add_f32_e32 v4, v115, v127
	v_add_f32_e32 v3, v3, v131
	v_add_f32_e32 v4, v4, v135
	v_add_f32_e32 v3, v3, v139
	v_add_f32_e32 v4, v4, v143
	v_add_f32_e32 v3, v3, v147
	v_add_f32_e32 v4, v4, v151
	v_add_f32_e32 v3, v3, v155
	v_add_f32_e32 v4, v4, v159
	v_add_f32_e32 v3, v3, v163
	v_add_f32_e32 v4, v4, v167
	v_add_f32_e32 v3, v3, v171
	v_add_f32_e32 v4, v4, v175
	v_add_f32_e32 v3, v3, v179
	v_add_f32_e32 v4, v4, v183
	v_add_f32_e32 v4, 1.0, v4
	v_mul_f32_e32 v4, v119, v4
	ds_write_b32 v1, v4 offset:38912
	ds_write_b32 v2, v3 offset:38912

; #define LAS __attribute__((address_space(3)))
; __device__ __forceinline__ int fresh_tid(int wave_s) { int z; asm volatile("s_mov_b32 %0, 0" : "=s"(z)); return wave_s * 64 + (int)__builtin_amdgcn_mbcnt_hi(~0u, __builtin_amdgcn_mbcnt_lo(~0u, (unsigned)z)); }
; __global__ void __launch_bounds__(512, 2) fwd_kernel(KP p) {
;     ...
;         __syncthreads();
;         { const int tid = fresh_tid(wave), lane = tid & 63; LAS float* b2s = (LAS float*)lds;
;           for (int e = tid; e < NSEQ * DM; e += 512) b2s[e] = MOD[(e / DM) * 12288 + 6144 + (e % DM)];
;           __syncthreads();
.LBB0_841:
	s_barrier
	s_mov_b32 s0, 0
	v_readlane_b32 s64, v253, 6
	v_mbcnt_lo_u32_b32 v0, -1, s0
	v_mbcnt_hi_u32_b32 v4, -1, v0
	v_add_u32_e32 v0, s64, v4
	s_movk_i32 s0, 0x2800
	v_cmp_gt_i32_e32 vcc, s0, v0
	s_and_saveexec_b64 s[0:1], vcc
	v_readlane_b32 s95, v254, 43
	s_cbranch_execz .LBB0_854
	v_lshlrev_b32_e32 v5, 2, v0
	s_add_u32 s4, s46, 0x6000
	s_addc_u32 s5, s47, 0
	global_load_dword v100, v5, s[4:5]
	global_load_dword v101, v5, s[4:5] offset:2048
	s_add_u32 s4, s46, 0x7000
	s_addc_u32 s5, s47, 0
	global_load_dword v102, v5, s[4:5]
	global_load_dword v103, v5, s[4:5] offset:2048
	s_add_u32 s4, s46, 0x12000
	s_addc_u32 s5, s47, 0
	global_load_dword v104, v5, s[4:5]
	global_load_dword v105, v5, s[4:5] offset:2048
	s_add_u32 s4, s46, 0x13000
	s_addc_u32 s5, s47, 0
	global_load_dword v106, v5, s[4:5]
	global_load_dword v107, v5, s[4:5] offset:2048
	s_add_u32 s4, s46, 0x1e000
	s_addc_u32 s5, s47, 0
	global_load_dword v108, v5, s[4:5]
	global_load_dword v109, v5, s[4:5] offset:2048
	s_add_u32 s4, s46, 0x1f000
	s_addc_u32 s5, s47, 0
	global_load_dword v110, v5, s[4:5]
	global_load_dword v111, v5, s[4:5] offset:2048
	s_add_u32 s4, s46, 0x2a000
	s_addc_u32 s5, s47, 0
	global_load_dword v112, v5, s[4:5]
	global_load_dword v113, v5, s[4:5] offset:2048
	s_add_u32 s4, s46, 0x2b000
	s_addc_u32 s5, s47, 0
	global_load_dword v114, v5, s[4:5]
	global_load_dword v115, v5, s[4:5] offset:2048
	s_add_u32 s4, s46, 0x36000
	s_addc_u32 s5, s47, 0
	global_load_dword v116, v5, s[4:5]
	global_load_dword v117, v5, s[4:5] offset:2048
	s_add_u32 s4, s46, 0x37000
	s_addc_u32 s5, s47, 0
	global_load_dword v118, v5, s[4:5]
	global_load_dword v119, v5, s[4:5] offset:2048
	s_waitcnt vmcnt(0)
	ds_write_b32 v5, v100
	ds_write_b32 v5, v101 offset:2048
	ds_write_b32 v5, v102 offset:4096
	ds_write_b32 v5, v103 offset:6144
	ds_write_b32 v5, v104 offset:8192
	ds_write_b32 v5, v105 offset:10240
	ds_write_b32 v5, v106 offset:12288
	ds_write_b32 v5, v107 offset:14336
	ds_write_b32 v5, v108 offset:16384
	ds_write_b32 v5, v109 offset:18432
	ds_write_b32 v5, v110 offset:20480
	ds_write_b32 v5, v111 offset:22528
	ds_write_b32 v5, v112 offset:24576
	ds_write_b32 v5, v113 offset:26624
	ds_write_b32 v5, v114 offset:28672
	ds_write_b32 v5, v115 offset:30720
	ds_write_b32 v5, v116 offset:32768
	ds_write_b32 v5, v117 offset:34816
	ds_write_b32 v5, v118 offset:36864
	ds_write_b32 v5, v119 offset:38912
